# v35 + stacked: SB unit-start K-fragment read hoist, packed-to-scalar f32 multiplies in SB (17) and SWA (30) loops
# speedup vs baseline: 1.0077x; 1.0077x over previous
; __device__ __forceinline__ unsigned pk2(float lo, float hi) { return pg8::cvt_pk_bf16(lo, hi); }
; __device__ __forceinline__ int crow(int r, int hi) { return (r & 3) + 8 * (r >> 2) + 4 * hi; }
; __device__ __forceinline__ void sb_mfma(const bf16_t* __restrict__ proj, bf16_t* __restrict__ mix, LAS unsigned char* ldsl) {
;     ...
;             u32x4 kf[4];
;             frag_read(kf, kimg, r32, hi);
;             f32x16 s;
; #pragma unroll
;             for (int r = 0; r < 16; ++r) s[r] = 0.f;
; #pragma unroll
;             for (int d0 = 0; d0 < 4; ++d0) s = __builtin_amdgcn_mfma_f32_32x32x16_bf16(as_bf(kf[d0]), as_bf(qf[d0]), s, 0, 0, 0);
;             const bool diag = (kb == t0);
;             float bt[16], kp1[16];
; #pragma unroll
;             for (int r = 0; r < 16; ++r) {
;                 const float z = fmaxf(s[r], -126.f);
;                 const float a = __builtin_amdgcn_exp2f(-z), rc = __builtin_amdgcn_rcpf(1.f + a);
;                 float be = rc, ke = a * rc;
;                 if (diag) { const bool valid = crow(r, hi) < r32; be = valid ? be : 0.f; ke = valid ? ke : 1.f; }
;                 bt[r] = be; kp1[r] = ke;
;             }
;             float gs[4], X[4];
; #pragma unroll
;             for (int c = 0; c < 4; ++c) { const float g4 = (kp1[4 * c] * kp1[4 * c + 1]) * (kp1[4 * c + 2] * kp1[4 * c + 3]); const HalfPair hp = half_swap(g4);
;                 gs[c] = hp.a * hp.b; X[c] = hi == 0 ? hp.b : 1.f; }
;             const float S2 = gs[3], S1 = S2 * gs[2], S0 = S1 * gs[1], total = S0 * gs[0];
;             const float SS[4] = {S0, S1, S2, 1.f};
;             float w[16];
; #pragma unroll
;             for (int c = 0; c < 4; ++c) {
;                 float run = A * SS[c] * X[c];
;                 w[4 * c + 3] = bt[4 * c + 3] * run; run *= kp1[4 * c + 3];
;                 w[4 * c + 2] = bt[4 * c + 2] * run; run *= kp1[4 * c + 2];
;                 w[4 * c + 1] = bt[4 * c + 1] * run; run *= kp1[4 * c + 1];
;                 w[4 * c + 0] = bt[4 * c + 0] * run;
;             }
;             A *= total;
;             u32x4 pb[2];
; #pragma unroll
;             for (int kk = 0; kk < 2; ++kk) { pb[kk].x = pk2(w[8 * kk], w[8 * kk + 1]); pb[kk].y = pk2(w[8 * kk + 2], w[8 * kk + 3]);
;                 pb[kk].z = pk2(w[8 * kk + 4], w[8 * kk + 5]); pb[kk].w = pk2(w[8 * kk + 6], w[8 * kk + 7]); }
.LBB0_274:
	s_waitcnt lgkmcnt(7)
	v_mfma_f32_32x32x16_bf16 v[0:15], v[118:121], v[48:51], 0
	s_waitcnt lgkmcnt(6)
	v_mfma_f32_32x32x16_bf16 v[0:15], v[110:113], v[52:55], v[0:15]
	s_waitcnt lgkmcnt(5)
	v_mfma_f32_32x32x16_bf16 v[0:15], v[122:125], v[56:59], v[0:15]
	s_waitcnt lgkmcnt(4)
	v_mfma_f32_32x32x16_bf16 v[0:15], v[114:117], v[60:63], v[0:15]
	s_nop 11
	v_max_f32_e64 v6, -v6, -v6
	v_min_f32_e32 v6, 0x42fc0000, v6
	v_exp_f32_e32 v6, v6
	v_max_f32_e64 v0, -v0, -v0
	v_min_f32_e32 v0, 0x42fc0000, v0
	v_exp_f32_e32 v0, v0
	v_add_f32_e32 v22, 1.0, v6
	v_rcp_f32_e32 v22, v22
	v_max_f32_e64 v1, -v1, -v1
	v_add_f32_e32 v16, 1.0, v0
	v_min_f32_e32 v1, 0x42fc0000, v1
	v_mul_f32_e32 v6, v6, v22
	v_cndmask_b32_e64 v23, 1.0, v6, s[16:17]
	v_max_f32_e64 v6, -v7, -v7
	v_min_f32_e32 v6, 0x42fc0000, v6
	v_exp_f32_e32 v6, v6
	v_rcp_f32_e32 v16, v16
	v_exp_f32_e32 v1, v1
	v_max_f32_e64 v2, -v2, -v2
	v_add_f32_e32 v7, 1.0, v6
	v_rcp_f32_e32 v7, v7
	v_mul_f32_e32 v17, v0, v16
	v_cndmask_b32_e64 v0, 0, v16, s[4:5]
	v_add_f32_e32 v16, 1.0, v1
	v_mul_f32_e32 v6, v6, v7
	v_cndmask_b32_e64 v25, 1.0, v6, s[18:19]
	v_max_f32_e64 v6, -v8, -v8
	v_min_f32_e32 v6, 0x42fc0000, v6
	v_exp_f32_e32 v6, v6
	v_cndmask_b32_e64 v24, 0, v7, s[18:19]
	v_rcp_f32_e32 v16, v16
	v_min_f32_e32 v2, 0x42fc0000, v2
	v_add_f32_e32 v7, 1.0, v6
	v_rcp_f32_e32 v7, v7
	v_exp_f32_e32 v2, v2
	v_mul_f32_e32 v18, v1, v16
	v_cndmask_b32_e64 v1, 0, v16, s[6:7]
	v_mul_f32_e32 v6, v6, v7
	v_cndmask_b32_e64 v27, 1.0, v6, s[20:21]
	v_max_f32_e64 v6, -v9, -v9
	v_min_f32_e32 v6, 0x42fc0000, v6
	v_exp_f32_e32 v6, v6
	v_cndmask_b32_e64 v26, 0, v7, s[20:21]
	v_cndmask_b32_e64 v16, 1.0, v18, s[6:7]
	v_add_f32_e32 v18, 1.0, v2
	v_add_f32_e32 v7, 1.0, v6
	v_rcp_f32_e32 v7, v7
	v_max_f32_e64 v3, -v3, -v3
	v_rcp_f32_e32 v18, v18
	v_min_f32_e32 v3, 0x42fc0000, v3
	v_mul_f32_e32 v6, v6, v7
	v_cndmask_b32_e64 v29, 1.0, v6, s[22:23]
	v_max_f32_e64 v6, -v10, -v10
	v_min_f32_e32 v6, 0x42fc0000, v6
	v_exp_f32_e32 v6, v6
	v_cndmask_b32_e64 v28, 0, v7, s[22:23]
	v_exp_f32_e32 v3, v3
	v_mul_f32_e32 v19, v2, v18
	v_add_f32_e32 v7, 1.0, v6
	v_rcp_f32_e32 v7, v7
	v_cndmask_b32_e64 v2, 0, v18, s[8:9]
	v_cndmask_b32_e64 v18, 1.0, v19, s[8:9]
	v_add_f32_e32 v19, 1.0, v3
	v_mul_f32_e32 v6, v6, v7
	v_cndmask_b32_e64 v31, 1.0, v6, s[24:25]
	v_max_f32_e64 v6, -v11, -v11
	v_min_f32_e32 v6, 0x42fc0000, v6
	v_exp_f32_e32 v6, v6
	v_cndmask_b32_e64 v30, 0, v7, s[24:25]
	v_max_f32_e64 v4, -v4, -v4
	v_rcp_f32_e32 v19, v19
	v_add_f32_e32 v7, 1.0, v6
	v_rcp_f32_e32 v7, v7
	v_min_f32_e32 v4, 0x42fc0000, v4
	v_exp_f32_e32 v4, v4
	v_mul_f32_e32 v20, v3, v19
	v_mul_f32_e32 v6, v6, v7
	v_cndmask_b32_e64 v33, 1.0, v6, s[26:27]
	v_max_f32_e64 v6, -v12, -v12
	v_min_f32_e32 v6, 0x42fc0000, v6
	v_exp_f32_e32 v6, v6
	v_cndmask_b32_e64 v32, 0, v7, s[26:27]
	v_cndmask_b32_e64 v3, 0, v19, s[10:11]
	v_cndmask_b32_e64 v19, 1.0, v20, s[10:11]
	v_add_f32_e32 v7, 1.0, v6
	v_rcp_f32_e32 v7, v7
	v_add_f32_e32 v20, 1.0, v4
	v_max_f32_e64 v5, -v5, -v5
	v_rcp_f32_e32 v20, v20
	v_mul_f32_e32 v6, v6, v7
	v_cndmask_b32_e64 v9, 1.0, v6, s[28:29]
	v_max_f32_e64 v6, -v13, -v13
	v_min_f32_e32 v6, 0x42fc0000, v6
	v_exp_f32_e32 v6, v6
	v_cndmask_b32_e64 v34, 0, v7, s[28:29]
	v_min_f32_e32 v5, 0x42fc0000, v5
	v_exp_f32_e32 v5, v5
	v_add_f32_e32 v7, 1.0, v6
	v_rcp_f32_e32 v7, v7
	v_mul_f32_e32 v21, v4, v20
	v_cndmask_b32_e64 v4, 0, v20, s[12:13]
	v_cndmask_b32_e64 v20, 1.0, v21, s[12:13]
	v_mul_f32_e32 v6, v6, v7
	v_cndmask_b32_e64 v36, 1.0, v6, s[30:31]
	v_max_f32_e64 v6, -v14, -v14
	v_min_f32_e32 v6, 0x42fc0000, v6
	v_exp_f32_e32 v6, v6
	v_cndmask_b32_e64 v35, 0, v7, s[30:31]
	v_add_f32_e32 v21, 1.0, v5
	v_rcp_f32_e32 v21, v21
	v_add_f32_e32 v7, 1.0, v6
	v_rcp_f32_e32 v7, v7
	v_cndmask_b32_e64 v17, 1.0, v17, s[4:5]
	v_mul_f32_e32 v5, v5, v21
	v_cndmask_b32_e64 v5, 1.0, v5, s[14:15]
	v_mul_f32_e32 v6, v6, v7
	v_cndmask_b32_e64 v37, 1.0, v6, s[34:35]
	v_max_f32_e64 v6, -v15, -v15
	v_min_f32_e32 v6, 0x42fc0000, v6
	v_exp_f32_e32 v6, v6
	v_cndmask_b32_e64 v14, 0, v7, s[34:35]
	v_mul_f32_e32 v10, v23, v25
	v_mul_f32_e32 v11, v31, v33
	v_add_f32_e32 v7, 1.0, v6
	v_rcp_f32_e32 v7, v7
	v_mul_f32_e32 v9, v9, v36
	v_cndmask_b32_e64 v22, 0, v22, s[16:17]
	v_cndmask_b32_e64 v21, 0, v21, s[14:15]
	v_mul_f32_e32 v6, v6, v7
	v_cndmask_b32_e64 v15, 1.0, v6, s[36:37]
	v_cndmask_b32_e64 v38, 0, v7, s[36:37]
	v_mul_f32_e32 v6, v17, v16
	v_mul_f32_e32 v7, v18, v19
	v_mul_f32_e32 v6, v6, v7
	v_mul_f32_e32 v7, v20, v5
	v_mul_f32_e32 v7, v7, v10
	v_mov_b32_e32 v10, v7
	s_nop 1
	v_permlane32_swap_b32_e32 v7, v10
	v_mul_f32_e32 v7, v7, v10
	v_cndmask_b32_e64 v20, 1.0, v10, s[0:1]
	v_mul_f32_e32 v10, v27, v29
	v_mul_f32_e32 v10, v10, v11
	v_mul_f32_e32 v11, v37, v15
	v_mul_f32_e32 v11, v9, v11
	v_mov_b32_e32 v12, v10
	v_mov_b32_e32 v13, v11
	s_nop 0
	v_permlane32_swap_b32_e32 v10, v12
	v_permlane32_swap_b32_e32 v11, v13
	v_mul_f32_e32 v10, v10, v12
	v_mul_f32_e32 v11, v11, v13
	v_mov_b32_e32 v8, v6
	v_cndmask_b32_e64 v27, 1.0, v12, s[0:1]
	v_cndmask_b32_e64 v39, 1.0, v13, s[0:1]
	v_pk_mul_f32 v[12:13], v[10:11], v[10:11] op_sel:[0,1] op_sel_hi:[1,0]
	v_permlane32_swap_b32_e32 v6, v8
	v_mov_b32_e32 v9, v12
	v_cndmask_b32_e64 v17, 1.0, v8, s[0:1]
	v_mul_f32_e32 v6, v6, v8
	v_mul_f32_e32 v7, v7, v9
	v_mul_f32_e32 v15, v39, v15
	v_mul_f32_e32 v8, v17, v7
	v_mul_f32_e32 v3, v3, v8
	v_mul_f32_e32 v8, v19, v8
	v_mul_f32_e32 v2, v2, v8
	v_mul_f32_e32 v8, v18, v8
	v_mul_f32_e32 v1, v1, v8
	v_mul_f32_e32 v8, v16, v8
	v_mul_f32_e32 v0, v0, v8
	v_mul_f32_e32 v8, v20, v12
	v_mul_f32_e32 v9, v24, v8
	v_mul_f32_e32 v8, v25, v8
	v_mul_f32_e32 v10, v22, v8
	v_mul_f32_e32 v8, v23, v8
	v_mul_f32_e32 v5, v5, v8
	v_mul_f32_e32 v4, v4, v5
	v_mul_f32_e32 v5, v27, v11
	v_mul_f32_e32 v12, v21, v8
	v_mul_f32_e32 v8, v32, v5
	v_mul_f32_e32 v5, v33, v5
	v_mul_f32_e32 v11, v30, v5
	v_mul_f32_e32 v5, v31, v5
	v_mul_f32_e32 v13, v28, v5
	v_mul_f32_e32 v5, v29, v5
	v_mul_f32_e32 v14, v14, v15
	v_mul_f32_e32 v15, v37, v15
	v_mul_f32_e32 v5, v26, v5
	v_mul_f32_e32 v17, v35, v15
	v_mul_f32_e32 v15, v36, v15
	v_mul_f32_e32 v16, v38, v39
	v_mul_f32_e32 v15, v34, v15
	v_mul_f32_e32 v101, v6, v7
	v_cvt_pk_bf16_f32 v0, v0, v1
	v_cvt_pk_bf16_f32 v1, v2, v3
	v_cvt_pk_bf16_f32 v2, v4, v12
	v_cvt_pk_bf16_f32 v3, v10, v9
	v_cvt_pk_bf16_f32 v32, v5, v13
	v_cvt_pk_bf16_f32 v33, v11, v8
	v_cvt_pk_bf16_f32 v34, v15, v17
	v_cvt_pk_bf16_f32 v35, v14, v16
	ds_read_b64_tr_b16 v[4:5], v108 offset:4608
	ds_read_b64_tr_b16 v[6:7], v108 offset:5760
	ds_read_b64_tr_b16 v[8:9], v108 offset:4672
	ds_read_b64_tr_b16 v[10:11], v108 offset:5824
	s_waitcnt lgkmcnt(2)
; #define LAS __attribute__((address_space(3)))
; __device__ __forceinline__ u32x2 tr_read(const LAS unsigned char* p) { return __builtin_bit_cast(u32x2, __builtin_amdgcn_ds_read_tr16_b64_v4i16((LAS v4i16_t*)p)); }
; __device__ __forceinline__ void pv_tile_tr(const LAS unsigned char* vimg, const u32x4 (&pb)[2], f32x16& o0, f32x16& o1, int r32, int hi) {
;     const int li = r32 & 15, dh = r32 >> 4;
;     const LAS unsigned char* base = vimg + (4 * hi + (li >> 2)) * 144 + (16 * dh + 4 * (li & 3)) * 2;
; #pragma unroll
;     for (int kk = 0; kk < 2; ++kk) {
;         const u32x2 l0 = tr_read(base + (16 * kk) * 144), h0 = tr_read(base + (16 * kk + 8) * 144);
;         const u32x2 l1 = tr_read(base + (16 * kk) * 144 + 64), h1 = tr_read(base + (16 * kk + 8) * 144 + 64);
;         const u32x4 va0 = {l0.x, l0.y, h0.x, h0.y}, va1 = {l1.x, l1.y, h1.x, h1.y};
;         o0 = __builtin_amdgcn_mfma_f32_32x32x16_bf16(as_bf(va0), as_bf(pb[kk]), o0, 0, 0, 0);
;         o1 = __builtin_amdgcn_mfma_f32_32x32x16_bf16(as_bf(va1), as_bf(pb[kk]), o1, 0, 0, 0);
;     }
; }
; __device__ __forceinline__ void sb_mfma(const bf16_t* __restrict__ proj, bf16_t* __restrict__ mix, LAS unsigned char* ldsl) {
;     ...
;             pv_tile_tr(vimg, pb, o0, o1, r32, hi);
;             if (__all(A < 1.17549435e-38f)) break;
	v_mfma_f32_32x32x16_bf16 v[16:31], v[4:7], v[0:3], 0
	ds_read_b64_tr_b16 v[36:37], v108 offset:6912
	ds_read_b64_tr_b16 v[38:39], v108 offset:8064
	ds_read_b64_tr_b16 v[40:41], v108 offset:6976
	ds_read_b64_tr_b16 v[42:43], v108 offset:8128
	v_cmp_gt_f32_e32 vcc, s3, v101
	s_cmp_eq_u64 vcc, exec
	s_cselect_b64 s[48:49], -1, 0
	s_cmp_eq_u32 s45, 0
	s_cselect_b64 s[50:51], -1, 0
	s_or_b64 s[48:49], s[50:51], s[48:49]
	s_waitcnt lgkmcnt(4)
	v_mfma_f32_32x32x16_bf16 v[0:15], v[8:11], v[0:3], 0
	s_and_b64 vcc, exec, s[48:49]
	s_mov_b32 s48, s45
	s_waitcnt lgkmcnt(2)
	v_mfma_f32_32x32x16_bf16 v[16:31], v[36:39], v[32:35], v[16:31]
	s_waitcnt lgkmcnt(0)
	v_mfma_f32_32x32x16_bf16 v[0:15], v[40:43], v[32:35], v[0:15]
	s_cbranch_vccz .LBB0_276
	s_branch .LBB0_271
